# combined: sample next-task prefetch + batched reduction, small_gemm<0> batched loads, next-unit SA(1,1) staged at epilogue start with relaxed first-iteration wait
# baseline (speedup 1.0000x reference)
.LBB0_824:
	v_or_b32_e32 v2, s16, v1
	v_lshlrev_b32_e32 v84, 11, v2
	v_or_b32_e32 v86, s17, v1
	v_mov_b32_e32 v85, v0
	v_ashrrev_i32_e32 v87, 31, v86
	v_lshl_add_u64 v[90:91], v[46:47], 0, v[84:85]
	s_mov_b32 s16, 0x8000
	v_lshlrev_b64 v[88:89], 11, v[86:87]
	v_add_co_u32_e32 v84, vcc, s16, v90
	v_or_b32_e32 v86, 32, v86
	v_lshl_add_u64 v[140:141], v[48:49], 0, v[88:89]
	v_addc_co_u32_e32 v85, vcc, 0, v91, vcc
	v_ashrrev_i32_e32 v87, 31, v86
	v_lshlrev_b64 v[86:87], 11, v[86:87]
	v_add_co_u32_e32 v142, vcc, s16, v140
	v_lshl_add_u64 v[88:89], v[48:49], 0, v[86:87]
	s_nop 0
	v_addc_co_u32_e32 v143, vcc, 0, v141, vcc
	v_add_co_u32_e32 v86, vcc, s16, v88
	s_nop 1
	v_addc_co_u32_e32 v87, vcc, 0, v89, vcc
	global_load_dwordx4 v[96:99], v[140:141], off
	global_load_dwordx4 v[112:115], v[90:91], off
	global_load_dwordx4 v[116:119], v[84:85], off
	global_load_dwordx4 v[100:103], v[88:89], off
	global_load_dwordx4 v[104:107], v[142:143], off
	global_load_dwordx4 v[108:111], v[86:87], off
	global_load_dwordx4 v[120:123], v[140:141], off offset:64
	global_load_dwordx4 v[136:139], v[90:91], off offset:64
	global_load_dwordx4 v[144:147], v[84:85], off offset:64
	global_load_dwordx4 v[124:127], v[88:89], off offset:64
	global_load_dwordx4 v[128:131], v[142:143], off offset:64
	global_load_dwordx4 v[132:135], v[86:87], off offset:64
	s_and_b64 vcc, exec, s[4:5]
	s_waitcnt vmcnt(0) lgkmcnt(0)
	v_mfma_f32_16x16x32_bf16 v[148:151], v[96:99], v[112:115], 0
	v_mfma_f32_16x16x32_bf16 v[152:155], v[96:99], v[116:119], 0
	v_mfma_f32_16x16x32_bf16 v[156:159], v[100:103], v[112:115], 0
	v_mfma_f32_16x16x32_bf16 v[160:163], v[100:103], v[116:119], 0
	v_mfma_f32_16x16x32_bf16 v[230:233], v[104:107], v[112:115], 0
	v_mfma_f32_16x16x32_bf16 v[234:237], v[104:107], v[116:119], 0
	v_mfma_f32_16x16x32_bf16 v[238:241], v[108:111], v[112:115], 0
	v_mfma_f32_16x16x32_bf16 v[242:245], v[108:111], v[116:119], 0
	v_mfma_f32_16x16x32_bf16 v[148:151], v[120:123], v[136:139], v[148:151]
	v_mfma_f32_16x16x32_bf16 v[152:155], v[120:123], v[144:147], v[152:155]
	v_mfma_f32_16x16x32_bf16 v[156:159], v[124:127], v[136:139], v[156:159]
	v_mfma_f32_16x16x32_bf16 v[160:163], v[124:127], v[144:147], v[160:163]
	v_mfma_f32_16x16x32_bf16 v[230:233], v[128:131], v[136:139], v[230:233]
	v_mfma_f32_16x16x32_bf16 v[234:237], v[128:131], v[144:147], v[234:237]
	v_mfma_f32_16x16x32_bf16 v[238:241], v[132:135], v[136:139], v[238:241]
	v_mfma_f32_16x16x32_bf16 v[242:245], v[132:135], v[144:147], v[242:245]
	global_load_dwordx4 v[96:99], v[140:141], off offset:128
	global_load_dwordx4 v[112:115], v[90:91], off offset:128
	global_load_dwordx4 v[116:119], v[84:85], off offset:128
	global_load_dwordx4 v[100:103], v[88:89], off offset:128
	global_load_dwordx4 v[104:107], v[142:143], off offset:128
	global_load_dwordx4 v[108:111], v[86:87], off offset:128
	global_load_dwordx4 v[120:123], v[140:141], off offset:192
	global_load_dwordx4 v[136:139], v[90:91], off offset:192
	global_load_dwordx4 v[144:147], v[84:85], off offset:192
	global_load_dwordx4 v[124:127], v[88:89], off offset:192
	global_load_dwordx4 v[128:131], v[142:143], off offset:192
	global_load_dwordx4 v[132:135], v[86:87], off offset:192
	s_waitcnt vmcnt(0)
	v_mfma_f32_16x16x32_bf16 v[148:151], v[96:99], v[112:115], v[148:151]
	v_mfma_f32_16x16x32_bf16 v[152:155], v[96:99], v[116:119], v[152:155]
	v_mfma_f32_16x16x32_bf16 v[156:159], v[100:103], v[112:115], v[156:159]
	v_mfma_f32_16x16x32_bf16 v[160:163], v[100:103], v[116:119], v[160:163]
	v_mfma_f32_16x16x32_bf16 v[230:233], v[104:107], v[112:115], v[230:233]
	v_mfma_f32_16x16x32_bf16 v[234:237], v[104:107], v[116:119], v[234:237]
	v_mfma_f32_16x16x32_bf16 v[238:241], v[108:111], v[112:115], v[238:241]
	v_mfma_f32_16x16x32_bf16 v[242:245], v[108:111], v[116:119], v[242:245]
	v_mfma_f32_16x16x32_bf16 v[148:151], v[120:123], v[136:139], v[148:151]
	v_mfma_f32_16x16x32_bf16 v[152:155], v[120:123], v[144:147], v[152:155]
	v_mfma_f32_16x16x32_bf16 v[156:159], v[124:127], v[136:139], v[156:159]
	v_mfma_f32_16x16x32_bf16 v[160:163], v[124:127], v[144:147], v[160:163]
	v_mfma_f32_16x16x32_bf16 v[230:233], v[128:131], v[136:139], v[230:233]
	v_mfma_f32_16x16x32_bf16 v[234:237], v[128:131], v[144:147], v[234:237]
	v_mfma_f32_16x16x32_bf16 v[238:241], v[132:135], v[136:139], v[238:241]
	v_mfma_f32_16x16x32_bf16 v[242:245], v[132:135], v[144:147], v[242:245]
	s_nop 7
	s_nop 1
	ds_write_b128 v94, v[148:151]
	ds_write_b128 v94, v[152:155] offset:2048
	ds_write_b128 v94, v[156:159] offset:4096
	ds_write_b128 v94, v[160:163] offset:6144
	ds_write_b128 v94, v[230:233] offset:16
	ds_write_b128 v94, v[234:237] offset:2064
	ds_write_b128 v94, v[238:241] offset:4112
	ds_write_b128 v94, v[242:245] offset:6160
	s_waitcnt lgkmcnt(0)
	s_barrier
	s_cbranch_vccnz .LBB0_826
	v_pk_add_f32 v[80:81], v[80:81], v[82:83]
	v_add_f32_e32 v82, v33, v31
	v_mov_b32_e32 v83, v81
	v_add_f32_e32 v84, v29, v27
	v_pk_add_f32 v[76:77], v[76:77], v[78:79]
	v_pk_add_f32 v[82:83], v[82:83], 0 op_sel_hi:[1,0]
	v_mov_b32_e32 v85, v80
	v_add_f32_e32 v78, v25, v23
	v_pk_add_f32 v[80:81], v[84:85], v[82:83]
	v_mov_b32_e32 v79, v77
	v_add_f32_e32 v86, v21, v19
	v_pk_add_f32 v[72:73], v[72:73], v[74:75]
	v_pk_add_f32 v[78:79], v[78:79], v[80:81]
	v_mov_b32_e32 v87, v76
	v_add_f32_e32 v74, v17, v15
	v_pk_add_f32 v[76:77], v[86:87], v[78:79]
	v_mov_b32_e32 v75, v73
	v_add_f32_e32 v88, v13, v11
	v_pk_add_f32 v[68:69], v[68:69], v[70:71]
	v_pk_add_f32 v[74:75], v[74:75], v[76:77]
	v_mov_b32_e32 v89, v72
	v_add_f32_e32 v70, v9, v7
	v_pk_add_f32 v[72:73], v[88:89], v[74:75]
	v_mov_b32_e32 v71, v69
	v_add_f32_e32 v90, v5, v3
	v_pk_add_f32 v[70:71], v[70:71], v[72:73]
	v_mov_b32_e32 v91, v68
	v_pk_add_f32 v[68:69], v[90:91], v[70:71]
	s_mov_b32 s4, 0x3a800000
	v_pk_mul_f32 v[68:69], v[68:69], s[4:5] op_sel_hi:[1,0]
	s_nop 0
	v_fma_f32 v2, -v69, v69, v68
	v_max_f32_e32 v2, 0, v2
	v_add_f32_e32 v2, 0x3727c5ac, v2
	v_mul_f32_e32 v4, 0x4b800000, v2
	v_cmp_gt_f32_e32 vcc, s83, v2
	s_nop 1
	v_cndmask_b32_e32 v2, v2, v4, vcc
	v_rsq_f32_e32 v2, v2
	s_nop 0
	v_mul_f32_e32 v4, 0x45800000, v2
	v_cndmask_b32_e32 v2, v2, v4, vcc
	v_mov_b32_e32 v4, v69
	s_branch .LBB0_827
